# v53 + up-phase second epilogue waves 0-3 block: its 32 gate loads pipelined 7 deep the same way (load order derived by emulating the address chain)
# speedup vs baseline: 1.0072x; 1.0072x over previous
; DI void gemm8_accum(f32x4 (&acc)[8][4], const bf16_t* a, size_t lda, const bf16_t* b, size_t ldb, int nkb, bf16_t* L,
;                     const bool pre, const bf16_t* an, size_t ldan, const bf16_t* bn, size_t ldbn) {
;     ...
;   __syncthreads();
;   g8_store1(L + 32768, ra, lrow, lch);
;   g8_load1(ra, an, ldan, 0, lrow, lch);
;   __builtin_amdgcn_sched_barrier(0);
;   g8_compute<0, 1>(acc, L, wm, wn, lane);
;   __builtin_amdgcn_sched_barrier(0);
;   g8_store1(L + 32768 + 16384, rb, lrow, lch);
;   g8_load1(rb, bn, ldbn, 0, lrow, lch);
;   __builtin_amdgcn_sched_barrier(0);
.Lstg_780_c:
	v_readlane_b32 s0, v254, 18
	s_add_i32 s21, s24, s0
	s_cmp_gt_u32 s21, 63
	s_cselect_b64 s[2:3], -1, 0
	s_cmp_lt_u32 s21, 64
	s_cselect_b32 s6, s21, s24
	s_lshl_b32 s0, s6, 1
	s_and_b32 s0, s0, 0x7fffffe0
	s_and_b32 s1, s6, 3
	s_or_b32 s0, s1, s0
	v_readlane_b32 s1, v252, 25
	s_or_b32 s28, s0, s1
	s_lshl_b32 s6, s6, 16
	s_lshl_b64 s[0:1], s[28:29], 18
	s_and_b32 s24, s6, 0xc0000
	v_readlane_b32 s6, v252, 39
	s_add_u32 s6, s6, s0
	v_readlane_b32 s0, v252, 40
	v_lshlrev_b32_e32 v163, 1, v163
	s_addc_u32 s7, s0, s1
	v_add3_u32 v172, s20, v191, v163
	s_barrier
	s_waitcnt vmcnt(7)
	ds_write_b128 v172, v[146:149]
	s_waitcnt vmcnt(6)
	ds_write_b128 v172, v[150:153] offset:8192
	s_waitcnt vmcnt(5)
	ds_write_b128 v172, v[154:157] offset:16384
	s_waitcnt vmcnt(4)
	ds_write_b128 v172, v[158:161] offset:24576
	v_lshl_add_u64 v[146:147], s[6:7], 0, v[164:165]
	v_lshl_add_u64 v[150:151], s[6:7], 0, v[166:167]
	v_lshl_add_u64 v[154:155], s[6:7], 0, v[168:169]
	v_lshl_add_u64 v[158:159], s[6:7], 0, v[170:171]
	global_load_dwordx4 v[146:149], v[146:147], off
	v_readlane_b32 s0, v252, 3
	global_load_dwordx4 v[150:153], v[150:151], off
	v_readlane_b32 s1, v252, 4
	global_load_dwordx4 v[154:157], v[154:155], off
	s_add_u32 s0, s0, s24
	global_load_dwordx4 v[158:161], v[158:159], off
	s_addc_u32 s1, s1, 0
	v_lshlrev_b32_e32 v202, 1, v192
	v_add_u32_e32 v203, 0, v202
	v_add_u32_e32 v204, v203, v189
	ds_read_b128 v[172:175], v204
	ds_read_b128 v[176:179], v204 offset:2048
	ds_read_b128 v[180:183], v204 offset:4096
	ds_read_b128 v[184:187], v204 offset:6144
	ds_read_b128 v[192:195], v204 offset:8192
	ds_read_b128 v[198:201], v204 offset:10240
	ds_read_b128 v[206:209], v204 offset:12288
	ds_read_b128 v[210:213], v204 offset:14336
	v_add_u32_e32 v203, v203, v188
	ds_read_b128 v[214:217], v203 offset:32768
	ds_read_b128 v[218:221], v203 offset:34816
	ds_read_b128 v[222:225], v203 offset:36864
	ds_read_b128 v[226:229], v203 offset:38912
	s_waitcnt lgkmcnt(3)
	v_mfma_f32_16x16x32_bf16 v[2:5], v[214:217], v[172:175], v[2:5]
	s_waitcnt lgkmcnt(2)
	v_mfma_f32_16x16x32_bf16 v[6:9], v[218:221], v[172:175], v[6:9]
	s_waitcnt lgkmcnt(1)
	v_mfma_f32_16x16x32_bf16 v[10:13], v[222:225], v[172:175], v[10:13]
	s_waitcnt lgkmcnt(0)
	v_mfma_f32_16x16x32_bf16 v[14:17], v[226:229], v[172:175], v[14:17]
	v_mfma_f32_16x16x32_bf16 v[22:25], v[214:217], v[176:179], v[22:25]
	v_mfma_f32_16x16x32_bf16 v[30:33], v[218:221], v[176:179], v[30:33]
	v_mfma_f32_16x16x32_bf16 v[38:41], v[222:225], v[176:179], v[38:41]
	v_mfma_f32_16x16x32_bf16 v[46:49], v[226:229], v[176:179], v[46:49]
	v_mfma_f32_16x16x32_bf16 v[54:57], v[214:217], v[180:183], v[54:57]
	v_mfma_f32_16x16x32_bf16 v[62:65], v[218:221], v[180:183], v[62:65]
	v_mfma_f32_16x16x32_bf16 v[70:73], v[222:225], v[180:183], v[70:73]
	v_mfma_f32_16x16x32_bf16 v[78:81], v[226:229], v[180:183], v[78:81]
	v_mfma_f32_16x16x32_bf16 v[86:89], v[214:217], v[184:187], v[86:89]
	v_mfma_f32_16x16x32_bf16 v[94:97], v[218:221], v[184:187], v[94:97]
	v_mfma_f32_16x16x32_bf16 v[102:105], v[222:225], v[184:187], v[102:105]
	v_mfma_f32_16x16x32_bf16 v[110:113], v[226:229], v[184:187], v[110:113]
	v_mfma_f32_16x16x32_bf16 v[118:121], v[214:217], v[192:195], v[118:121]
	v_mfma_f32_16x16x32_bf16 v[126:129], v[218:221], v[192:195], v[126:129]
	v_mfma_f32_16x16x32_bf16 v[122:125], v[222:225], v[192:195], v[122:125]
	v_mfma_f32_16x16x32_bf16 v[114:117], v[226:229], v[192:195], v[114:117]
	v_mfma_f32_16x16x32_bf16 v[106:109], v[214:217], v[198:201], v[106:109]
	v_mfma_f32_16x16x32_bf16 v[98:101], v[218:221], v[198:201], v[98:101]
	v_mfma_f32_16x16x32_bf16 v[90:93], v[222:225], v[198:201], v[90:93]
	v_mfma_f32_16x16x32_bf16 v[82:85], v[226:229], v[198:201], v[82:85]
	v_mfma_f32_16x16x32_bf16 v[74:77], v[214:217], v[206:209], v[74:77]
	v_mfma_f32_16x16x32_bf16 v[66:69], v[218:221], v[206:209], v[66:69]
	v_mfma_f32_16x16x32_bf16 v[58:61], v[222:225], v[206:209], v[58:61]
	v_mfma_f32_16x16x32_bf16 v[50:53], v[226:229], v[206:209], v[50:53]
	v_mfma_f32_16x16x32_bf16 v[42:45], v[214:217], v[210:213], v[42:45]
	v_mfma_f32_16x16x32_bf16 v[34:37], v[218:221], v[210:213], v[34:37]
	v_mfma_f32_16x16x32_bf16 v[26:29], v[222:225], v[210:213], v[26:29]
	v_mfma_f32_16x16x32_bf16 v[18:21], v[226:229], v[210:213], v[18:21]
	v_readlane_b32 s6, v254, 36
	s_nop 1
	v_add3_u32 v163, s6, v191, v163
	s_waitcnt vmcnt(7)
	ds_write_b128 v163, v[130:133]
	s_waitcnt vmcnt(6)
	ds_write_b128 v163, v[138:141] offset:8192
	s_waitcnt vmcnt(5)
	ds_write_b128 v163, v[134:137] offset:16384
	s_waitcnt vmcnt(4)
	ds_write_b128 v163, v[142:145] offset:24576
	v_lshl_add_u64 v[130:131], s[0:1], 0, v[164:165]
	v_lshl_add_u64 v[138:139], s[0:1], 0, v[168:169]
	global_load_dwordx4 v[130:133], v[130:131], off
	v_lshl_add_u64 v[134:135], s[0:1], 0, v[166:167]
	global_load_dwordx4 v[138:141], v[138:139], off
	v_lshl_add_u64 v[142:143], s[0:1], 0, v[170:171]
	global_load_dwordx4 v[134:137], v[134:135], off
	s_nop 0
	global_load_dwordx4 v[142:145], v[142:143], off
	v_lshlrev_b32_e32 v163, 1, v190
	v_add_u32_e32 v194, 0, v163
	v_add_u32_e32 v195, v194, v189
	ds_read_b128 v[164:167], v195
	ds_read_b128 v[168:171], v195 offset:2048
	ds_read_b128 v[172:175], v195 offset:4096
	ds_read_b128 v[176:179], v195 offset:6144
	ds_read_b128 v[180:183], v195 offset:8192
	ds_read_b128 v[184:187], v195 offset:10240
	ds_read_b128 v[190:193], v195 offset:12288
	ds_read_b128 v[198:201], v195 offset:14336
	v_add_u32_e32 v194, v194, v188
	ds_read_b128 v[206:209], v194 offset:32768
	ds_read_b128 v[210:213], v194 offset:34816
	ds_read_b128 v[214:217], v194 offset:36864
	ds_read_b128 v[218:221], v194 offset:38912
	s_waitcnt lgkmcnt(3)
; DI void gemm8_accum(f32x4 (&acc)[8][4], const bf16_t* a, size_t lda, const bf16_t* b, size_t ldb, int nkb, bf16_t* L,
;                     const bool pre, const bf16_t* an, size_t ldan, const bf16_t* bn, size_t ldbn) {
;     ...
;   g8_compute<1, 2>(acc, L, wm, wn, lane);
;   __syncthreads();
;   g8_store1(L, ra, lrow, lch);
;   __builtin_amdgcn_sched_barrier(0);
;   g8_compute<0, 1>(acc, L + 32768, wm, wn, lane);
;   __builtin_amdgcn_sched_barrier(0);
;   g8_store1(L + 16384, rb, lrow, lch);
	v_mfma_f32_16x16x32_bf16 v[2:5], v[206:209], v[164:167], v[2:5]
	s_waitcnt lgkmcnt(2)
	v_mfma_f32_16x16x32_bf16 v[6:9], v[210:213], v[164:167], v[6:9]
	s_waitcnt lgkmcnt(1)
	v_mfma_f32_16x16x32_bf16 v[10:13], v[214:217], v[164:167], v[10:13]
	s_waitcnt lgkmcnt(0)
	v_mfma_f32_16x16x32_bf16 v[14:17], v[218:221], v[164:167], v[14:17]
	v_mfma_f32_16x16x32_bf16 v[22:25], v[206:209], v[168:171], v[22:25]
	v_mfma_f32_16x16x32_bf16 v[30:33], v[210:213], v[168:171], v[30:33]
	v_mfma_f32_16x16x32_bf16 v[38:41], v[214:217], v[168:171], v[38:41]
	v_mfma_f32_16x16x32_bf16 v[46:49], v[218:221], v[168:171], v[46:49]
	v_mfma_f32_16x16x32_bf16 v[54:57], v[206:209], v[172:175], v[54:57]
	v_mfma_f32_16x16x32_bf16 v[62:65], v[210:213], v[172:175], v[62:65]
	v_mfma_f32_16x16x32_bf16 v[70:73], v[214:217], v[172:175], v[70:73]
	v_mfma_f32_16x16x32_bf16 v[78:81], v[218:221], v[172:175], v[78:81]
	v_mfma_f32_16x16x32_bf16 v[86:89], v[206:209], v[176:179], v[86:89]
	v_mfma_f32_16x16x32_bf16 v[94:97], v[210:213], v[176:179], v[94:97]
	v_mfma_f32_16x16x32_bf16 v[102:105], v[214:217], v[176:179], v[102:105]
	v_mfma_f32_16x16x32_bf16 v[110:113], v[218:221], v[176:179], v[110:113]
	v_mfma_f32_16x16x32_bf16 v[118:121], v[206:209], v[180:183], v[118:121]
	v_mfma_f32_16x16x32_bf16 v[126:129], v[210:213], v[180:183], v[126:129]
	v_mfma_f32_16x16x32_bf16 v[122:125], v[214:217], v[180:183], v[122:125]
	v_mfma_f32_16x16x32_bf16 v[114:117], v[218:221], v[180:183], v[114:117]
	v_mfma_f32_16x16x32_bf16 v[106:109], v[206:209], v[184:187], v[106:109]
	v_mfma_f32_16x16x32_bf16 v[98:101], v[210:213], v[184:187], v[98:101]
	v_mfma_f32_16x16x32_bf16 v[90:93], v[214:217], v[184:187], v[90:93]
	v_mfma_f32_16x16x32_bf16 v[82:85], v[218:221], v[184:187], v[82:85]
	v_mfma_f32_16x16x32_bf16 v[74:77], v[206:209], v[190:193], v[74:77]
	v_mfma_f32_16x16x32_bf16 v[66:69], v[210:213], v[190:193], v[66:69]
	v_mfma_f32_16x16x32_bf16 v[58:61], v[214:217], v[190:193], v[58:61]
	v_mfma_f32_16x16x32_bf16 v[50:53], v[218:221], v[190:193], v[50:53]
	v_mfma_f32_16x16x32_bf16 v[42:45], v[206:209], v[198:201], v[42:45]
	v_mfma_f32_16x16x32_bf16 v[34:37], v[210:213], v[198:201], v[34:37]
	v_mfma_f32_16x16x32_bf16 v[26:29], v[214:217], v[198:201], v[26:29]
	v_mfma_f32_16x16x32_bf16 v[18:21], v[218:221], v[198:201], v[18:21]
	s_barrier
	s_waitcnt vmcnt(7)
	ds_write_b128 v0, v[146:149]
	s_waitcnt vmcnt(6)
	ds_write_b128 v0, v[150:153] offset:8192
	s_waitcnt vmcnt(5)
	ds_write_b128 v0, v[154:157] offset:16384
	s_waitcnt vmcnt(4)
	ds_write_b128 v0, v[158:161] offset:24576
	v_add3_u32 v176, s20, v202, v189
	ds_read_b128 v[146:149], v176
	ds_read_b128 v[150:153], v176 offset:2048
	ds_read_b128 v[154:157], v176 offset:4096
	ds_read_b128 v[158:161], v176 offset:6144
	ds_read_b128 v[164:167], v176 offset:8192
	ds_read_b128 v[168:171], v176 offset:10240
	ds_read_b128 v[172:175], v176 offset:12288
	ds_read_b128 v[176:179], v176 offset:14336
	v_add3_u32 v194, s6, v202, v188
	ds_read_b128 v[180:183], v194
	ds_read_b128 v[184:187], v194 offset:2048
	ds_read_b128 v[190:193], v194 offset:4096
	ds_read_b128 v[198:201], v194 offset:6144
	s_waitcnt lgkmcnt(3)
	v_mfma_f32_16x16x32_bf16 v[2:5], v[180:183], v[146:149], v[2:5]
	s_waitcnt lgkmcnt(2)
	v_mfma_f32_16x16x32_bf16 v[6:9], v[184:187], v[146:149], v[6:9]
	s_waitcnt lgkmcnt(1)
	v_mfma_f32_16x16x32_bf16 v[10:13], v[190:193], v[146:149], v[10:13]
	s_waitcnt lgkmcnt(0)
	v_mfma_f32_16x16x32_bf16 v[14:17], v[198:201], v[146:149], v[14:17]
	v_mfma_f32_16x16x32_bf16 v[22:25], v[180:183], v[150:153], v[22:25]
	v_mfma_f32_16x16x32_bf16 v[30:33], v[184:187], v[150:153], v[30:33]
	v_mfma_f32_16x16x32_bf16 v[38:41], v[190:193], v[150:153], v[38:41]
	v_mfma_f32_16x16x32_bf16 v[46:49], v[198:201], v[150:153], v[46:49]
	v_mfma_f32_16x16x32_bf16 v[54:57], v[180:183], v[154:157], v[54:57]
	v_mfma_f32_16x16x32_bf16 v[62:65], v[184:187], v[154:157], v[62:65]
	v_mfma_f32_16x16x32_bf16 v[70:73], v[190:193], v[154:157], v[70:73]
	v_mfma_f32_16x16x32_bf16 v[78:81], v[198:201], v[154:157], v[78:81]
	v_mfma_f32_16x16x32_bf16 v[146:149], v[180:183], v[158:161], v[86:89]
	v_mfma_f32_16x16x32_bf16 v[150:153], v[184:187], v[158:161], v[94:97]
	v_mfma_f32_16x16x32_bf16 v[154:157], v[190:193], v[158:161], v[102:105]
	v_mfma_f32_16x16x32_bf16 v[158:161], v[198:201], v[158:161], v[110:113]
	v_mfma_f32_16x16x32_bf16 v[206:209], v[180:183], v[164:167], v[118:121]
	v_mfma_f32_16x16x32_bf16 v[210:213], v[184:187], v[164:167], v[126:129]
	v_mfma_f32_16x16x32_bf16 v[214:217], v[190:193], v[164:167], v[122:125]
	v_mfma_f32_16x16x32_bf16 v[164:167], v[198:201], v[164:167], v[114:117]
	v_mfma_f32_16x16x32_bf16 v[218:221], v[180:183], v[168:171], v[106:109]
	v_mfma_f32_16x16x32_bf16 v[222:225], v[184:187], v[168:171], v[98:101]
	v_mfma_f32_16x16x32_bf16 v[226:229], v[190:193], v[168:171], v[90:93]
	v_mfma_f32_16x16x32_bf16 v[168:171], v[198:201], v[168:171], v[82:85]
	v_mfma_f32_16x16x32_bf16 v[230:233], v[180:183], v[172:175], v[74:77]
	v_mfma_f32_16x16x32_bf16 v[234:237], v[184:187], v[172:175], v[66:69]
	v_mfma_f32_16x16x32_bf16 v[238:241], v[190:193], v[172:175], v[58:61]
	v_mfma_f32_16x16x32_bf16 v[172:175], v[198:201], v[172:175], v[50:53]
	v_mfma_f32_16x16x32_bf16 v[180:183], v[180:183], v[176:179], v[42:45]
	v_mfma_f32_16x16x32_bf16 v[184:187], v[184:187], v[176:179], v[34:37]
	v_mfma_f32_16x16x32_bf16 v[190:193], v[190:193], v[176:179], v[26:29]
	v_mfma_f32_16x16x32_bf16 v[176:179], v[198:201], v[176:179], v[18:21]
	s_waitcnt vmcnt(3)
	ds_write_b128 v0, v[130:133] offset:32768
	s_waitcnt vmcnt(1)
	ds_write_b128 v0, v[134:137] offset:40960
	ds_write_b128 v0, v[138:141] offset:49152
	s_waitcnt vmcnt(0)
; DI float bflo(unsigned u) { return __uint_as_float(u << 16); }
; DI float bfhi(unsigned u) { return __uint_as_float(u & 0xffff0000u); }
; DI float sigmoidf(float x) { return __builtin_amdgcn_rcpf(1.f + __expf(-x)); }
; DI int TID8() { int t = threadIdx.x; asm volatile("" : "+v"(t)); return t; }
; DI void gemm8_accum(f32x4 (&acc)[8][4], const bf16_t* a, size_t lda, const bf16_t* b, size_t ldb, int nkb, bf16_t* L,
;                     const bool pre, const bf16_t* an, size_t ldan, const bf16_t* bn, size_t ldbn) {
;     ...
;   g8_compute<0, 1>(acc, L + 32768, wm, wn, lane);
;   __builtin_amdgcn_sched_barrier(0);
;   g8_store1(L + 16384, rb, lrow, lch);
;   __builtin_amdgcn_sched_barrier(0);
;   g8_compute<1, 2>(acc, L + 32768, wm, wn, lane);
;   __syncthreads();
; }
; DI void zero_acc8(f32x4 (&acc)[8][4]) {
; #pragma unroll
;   for (int i = 0; i < 8; ++i)
; #pragma unroll
;     for (int j = 0; j < 4; ++j) acc[i][j] = f32x4{0.f, 0.f, 0.f, 0.f};
; }
; template <class F>
; DI void gemm8_epi_staged(f32x4 (&acc)[8][4], int m0, int n0, bf16_t* L0, F f, bf16_t* dst, size_t ld, int nmax) {
;   bf16_t* L = L0 + 32768;
;   const int tid = TID8(), lane = tid & 63, w = tid >> 6;
;   const int wm = w >> 2, wn = w & 3;
; #pragma unroll
;   for (int half = 0; half < 2; ++half) {
;     if (wm == half) {
; #pragma unroll
;       for (int i = 0; i < 8; ++i)
; #pragma unroll
;         for (int j = 0; j < 4; ++j) {
;           const int ml = i * 16 + (lane & 15);
;           const int nl = wn * 64 + j * 16 + (lane >> 4) * 4;
;           f32x4 a = acc[i][j];
;           f(m0 + half * 128 + ml, n0 + nl, a);
;           uint2 u;
;           u.x = pack2(a[0], a[1]);
;           u.y = pack2(a[2], a[3]);
;           *(uint2*)(L + ml * 264 + nl) = u;
;         }
; __global__ void __launch_bounds__(512, 2) mega(Params p) {
;     ...
;       gemm8_epi_staged(acc8, m0, n0, lds_all, [&](int m, int n, f32x4& a) {
;         uint2 ub = *(const uint2*)(z + (size_t)m * ZS + C_MB + n);
;         a[0] *= sigmoidf(bflo(ub.x)); a[1] *= sigmoidf(bfhi(ub.x));
;         a[2] *= sigmoidf(bflo(ub.y)); a[3] *= sigmoidf(bfhi(ub.y));
;       }, z + C_RK, ZS, 1024);
	ds_write_b128 v0, v[142:145] offset:57344
	v_add3_u32 v0, s20, v163, v189
	ds_read_b128 v[18:21], v0
	ds_read_b128 v[26:29], v0 offset:2048
	ds_read_b128 v[34:37], v0 offset:4096
	ds_read_b128 v[42:45], v0 offset:6144
	ds_read_b128 v[50:53], v0 offset:8192
	ds_read_b128 v[130:133], v0 offset:10240
	ds_read_b128 v[134:137], v0 offset:12288
	ds_read_b128 v[138:141], v0 offset:14336
	v_add3_u32 v0, s6, v163, v188
	ds_read_b128 v[142:145], v0
	ds_read_b128 v[198:201], v0 offset:2048
	ds_read_b128 v[242:245], v0 offset:4096
	ds_read_b128 v[246:249], v0 offset:6144
	s_waitcnt lgkmcnt(3)
	v_mfma_f32_16x16x32_bf16 v[126:129], v[142:145], v[18:21], v[2:5]
	s_waitcnt lgkmcnt(2)
	v_mfma_f32_16x16x32_bf16 v[122:125], v[198:201], v[18:21], v[6:9]
	s_waitcnt lgkmcnt(1)
	v_mfma_f32_16x16x32_bf16 v[118:121], v[242:245], v[18:21], v[10:13]
	s_waitcnt lgkmcnt(0)
	v_mfma_f32_16x16x32_bf16 v[114:117], v[246:249], v[18:21], v[14:17]
	v_mfma_f32_16x16x32_bf16 v[110:113], v[142:145], v[26:29], v[22:25]
	v_mfma_f32_16x16x32_bf16 v[106:109], v[198:201], v[26:29], v[30:33]
	v_mfma_f32_16x16x32_bf16 v[102:105], v[242:245], v[26:29], v[38:41]
	v_mfma_f32_16x16x32_bf16 v[98:101], v[246:249], v[26:29], v[46:49]
	v_mfma_f32_16x16x32_bf16 v[94:97], v[142:145], v[34:37], v[54:57]
	v_mfma_f32_16x16x32_bf16 v[90:93], v[198:201], v[34:37], v[62:65]
	v_mfma_f32_16x16x32_bf16 v[86:89], v[242:245], v[34:37], v[70:73]
	v_mfma_f32_16x16x32_bf16 v[82:85], v[246:249], v[34:37], v[78:81]
	v_mfma_f32_16x16x32_bf16 v[78:81], v[142:145], v[42:45], v[146:149]
	v_mfma_f32_16x16x32_bf16 v[74:77], v[198:201], v[42:45], v[150:153]
	v_mfma_f32_16x16x32_bf16 v[70:73], v[242:245], v[42:45], v[154:157]
	v_mfma_f32_16x16x32_bf16 v[66:69], v[246:249], v[42:45], v[158:161]
	v_mfma_f32_16x16x32_bf16 v[62:65], v[142:145], v[50:53], v[206:209]
	v_mfma_f32_16x16x32_bf16 v[58:61], v[198:201], v[50:53], v[210:213]
	v_mfma_f32_16x16x32_bf16 v[54:57], v[242:245], v[50:53], v[214:217]
	v_mfma_f32_16x16x32_bf16 v[50:53], v[246:249], v[50:53], v[164:167]
	v_mfma_f32_16x16x32_bf16 v[46:49], v[142:145], v[130:133], v[218:221]
	v_mfma_f32_16x16x32_bf16 v[42:45], v[198:201], v[130:133], v[222:225]
	v_mfma_f32_16x16x32_bf16 v[38:41], v[242:245], v[130:133], v[226:229]
	v_mfma_f32_16x16x32_bf16 v[34:37], v[246:249], v[130:133], v[168:171]
	v_mfma_f32_16x16x32_bf16 v[30:33], v[142:145], v[134:137], v[230:233]
	v_mfma_f32_16x16x32_bf16 v[26:29], v[198:201], v[134:137], v[234:237]
	v_mfma_f32_16x16x32_bf16 v[22:25], v[242:245], v[134:137], v[238:241]
	v_mfma_f32_16x16x32_bf16 v[18:21], v[246:249], v[134:137], v[172:175]
	v_mfma_f32_16x16x32_bf16 v[14:17], v[142:145], v[138:141], v[180:183]
	v_mfma_f32_16x16x32_bf16 v[10:13], v[198:201], v[138:141], v[184:187]
	v_mfma_f32_16x16x32_bf16 v[6:9], v[242:245], v[138:141], v[190:193]
	v_mfma_f32_16x16x32_bf16 v[2:5], v[246:249], v[138:141], v[176:179]
	v_mov_b32_e32 v140, v196
	s_barrier
	s_movk_i32 s0, 0x100
	v_and_b32_e32 v0, 0xc0, v140
	v_lshrrev_b32_e32 v130, 2, v140
	v_and_b32_e32 v139, 15, v140
	v_and_or_b32 v0, v130, 12, v0
	v_mul_u32_u24_e32 v131, 0x210, v139
	v_or_b32_e32 v130, s12, v0
	v_lshlrev_b32_e32 v0, 1, v0
	v_cmp_gt_u32_e32 vcc, s0, v140
	v_lshlrev_b32_e32 v130, 1, v130
	v_add3_u32 v138, s20, v131, v0
	s_and_saveexec_b64 s[0:1], vcc
	s_cbranch_execz .LBB0_783
	v_or_b32_e32 v141, s13, v139
	v_mul_u32_u24_e32 v0, 0x2a30, v141
	v_lshl_add_u64 v[132:133], s[16:17], 0, v[0:1]
	s_mov_b64 s[6:7], 0x2230
	v_lshl_add_u64 v[136:137], v[132:133], 0, s[6:7]
	v_mov_b32_e32 v131, v1
	v_lshl_add_u64 v[132:133], v[136:137], 0, v[130:131]
	s_nop 0
	v_readfirstlane_b32 s86, v132
	v_readfirstlane_b32 s87, v133
	s_sub_u32 s86, s86, 0x40000000
	s_subb_u32 s87, s87, 0
	v_subrev_u32_e32 v163, s86, v132
	global_load_dwordx2 v[150:151], v163, s[86:87]
	global_load_dwordx2 v[152:153], v163, s[86:87] offset:32
	global_load_dwordx2 v[154:155], v163, s[86:87] offset:64
	global_load_dwordx2 v[156:157], v163, s[86:87] offset:96
	s_add_u32 s86, s86, 0x2a300
	s_addc_u32 s87, s87, 0
	global_load_dwordx2 v[160:161], v163, s[86:87]
	global_load_dwordx2 v[188:189], v163, s[86:87] offset:32
	global_load_dwordx2 v[190:191], v163, s[86:87] offset:64
	s_waitcnt vmcnt(6)
	v_mov_b64_e32 v[132:133], v[150:151]
	global_load_dwordx2 v[150:151], v163, s[86:87] offset:96
	v_add_u32_e32 v148, 0x4000, v138
	v_lshlrev_b32_e32 v0, 16, v132
	v_mul_f32_e32 v0, 0xbfb8aa3b, v0
	v_exp_f32_e32 v0, v0
	s_nop 0
	v_add_f32_e32 v0, 1.0, v0
	v_rcp_f32_e32 v134, v0
	v_and_b32_e32 v0, 0xffff0000, v132
	v_mul_f32_e32 v0, 0xbfb8aa3b, v0
	v_exp_f32_e32 v0, v0
	s_nop 0
	v_add_f32_e32 v0, 1.0, v0
	v_rcp_f32_e32 v135, v0
	v_lshlrev_b32_e32 v0, 16, v133
	v_mul_f32_e32 v0, 0xbfb8aa3b, v0
	v_exp_f32_e32 v0, v0
	v_pk_mul_f32 v[134:135], v[126:127], v[134:135]
	v_add_f32_e32 v0, 1.0, v0
	v_rcp_f32_e32 v132, v0
	v_and_b32_e32 v0, 0xffff0000, v133
	v_mul_f32_e32 v0, 0xbfb8aa3b, v0
	v_exp_f32_e32 v0, v0
	v_cvt_pk_bf16_f32 v134, v134, v135
	v_add_f32_e32 v0, 1.0, v0
	v_rcp_f32_e32 v133, v0
	v_or_b32_e32 v0, 32, v130
	v_pk_mul_f32 v[132:133], v[128:129], v[132:133]
	s_nop 0
	v_cvt_pk_bf16_f32 v135, v132, v133
	v_lshl_add_u64 v[132:133], v[136:137], 0, v[0:1]
	s_waitcnt vmcnt(6)
; DI float bflo(unsigned u) { return __uint_as_float(u << 16); }
; DI float bfhi(unsigned u) { return __uint_as_float(u & 0xffff0000u); }
; DI float sigmoidf(float x) { return __builtin_amdgcn_rcpf(1.f + __expf(-x)); }
; template <class F>
; DI void gemm8_epi_staged(f32x4 (&acc)[8][4], int m0, int n0, bf16_t* L0, F f, bf16_t* dst, size_t ld, int nmax) {
;     ...
;       for (int i = 0; i < 8; ++i)
; #pragma unroll
;         for (int j = 0; j < 4; ++j) {
;           const int ml = i * 16 + (lane & 15);
;           const int nl = wn * 64 + j * 16 + (lane >> 4) * 4;
;           f32x4 a = acc[i][j];
;           f(m0 + half * 128 + ml, n0 + nl, a);
;           uint2 u;
;           u.x = pack2(a[0], a[1]);
;           u.y = pack2(a[2], a[3]);
;           *(uint2*)(L + ml * 264 + nl) = u;
;         }
; __global__ void __launch_bounds__(512, 2) mega(Params p) {
;     ...
;       gemm8_epi_staged(acc8, m0, n0, lds_all, [&](int m, int n, f32x4& a) {
;         uint2 ub = *(const uint2*)(z + (size_t)m * ZS + C_MB + n);
;         a[0] *= sigmoidf(bflo(ub.x)); a[1] *= sigmoidf(bfhi(ub.x));
;         a[2] *= sigmoidf(bflo(ub.y)); a[3] *= sigmoidf(bfhi(ub.y));
;       }, z + C_RK, ZS, 1024);
	v_mov_b64_e32 v[132:133], v[152:153]
	s_add_u32 s86, s86, 0x2a300
	s_addc_u32 s87, s87, 0
	global_load_dwordx2 v[152:153], v163, s[86:87]
	v_lshlrev_b32_e32 v142, 16, v132
	v_and_b32_e32 v132, 0xffff0000, v132
	v_mul_f32_e32 v132, 0xbfb8aa3b, v132
	v_exp_f32_e32 v132, v132
	v_mul_f32_e32 v142, 0xbfb8aa3b, v142
	v_exp_f32_e32 v142, v142
	v_add_f32_e32 v132, 1.0, v132
	v_rcp_f32_e32 v143, v132
	v_lshlrev_b32_e32 v132, 16, v133
	v_and_b32_e32 v133, 0xffff0000, v133
	v_mul_f32_e32 v132, 0xbfb8aa3b, v132
	v_mul_f32_e32 v133, 0xbfb8aa3b, v133
	v_exp_f32_e32 v132, v132
	v_exp_f32_e32 v133, v133
	v_add_f32_e32 v142, 1.0, v142
	v_rcp_f32_e32 v142, v142
	v_add_f32_e32 v132, 1.0, v132
	v_add_f32_e32 v133, 1.0, v133
	v_rcp_f32_e32 v132, v132
	v_rcp_f32_e32 v133, v133
	v_pk_mul_f32 v[142:143], v[122:123], v[142:143]
	v_pk_mul_f32 v[132:133], v[124:125], v[132:133]
	v_cvt_pk_bf16_f32 v142, v142, v143
	v_cvt_pk_bf16_f32 v143, v132, v133
	ds_write2_b64 v138, v[134:135], v[142:143] offset1:4
	v_or_b32_e32 v134, 64, v130
	v_mov_b32_e32 v135, v1
	v_lshl_add_u64 v[132:133], v[136:137], 0, v[134:135]
	s_waitcnt vmcnt(6)
	v_mov_b64_e32 v[132:133], v[154:155]
	global_load_dwordx2 v[154:155], v163, s[86:87] offset:32
	v_lshlrev_b32_e32 v142, 16, v132
	v_and_b32_e32 v132, 0xffff0000, v132
	v_mul_f32_e32 v132, 0xbfb8aa3b, v132
	v_exp_f32_e32 v132, v132
	v_mul_f32_e32 v142, 0xbfb8aa3b, v142
	v_exp_f32_e32 v142, v142
	v_add_f32_e32 v132, 1.0, v132
	v_rcp_f32_e32 v143, v132
	v_lshlrev_b32_e32 v132, 16, v133
	v_and_b32_e32 v133, 0xffff0000, v133
	v_mul_f32_e32 v132, 0xbfb8aa3b, v132
	v_mul_f32_e32 v133, 0xbfb8aa3b, v133
	v_exp_f32_e32 v132, v132
	v_exp_f32_e32 v133, v133
	v_add_f32_e32 v142, 1.0, v142
	v_rcp_f32_e32 v142, v142
	v_add_f32_e32 v132, 1.0, v132
	v_add_f32_e32 v133, 1.0, v133
	v_rcp_f32_e32 v132, v132
	v_rcp_f32_e32 v133, v133
	v_pk_mul_f32 v[142:143], v[118:119], v[142:143]
	v_pk_mul_f32 v[132:133], v[120:121], v[132:133]
	v_cvt_pk_bf16_f32 v142, v142, v143
	v_cvt_pk_bf16_f32 v143, v132, v133
	v_or_b32_e32 v132, 0x60, v130
	v_mov_b32_e32 v133, v1
	v_lshl_add_u64 v[136:137], v[136:137], 0, v[132:133]
	s_waitcnt vmcnt(6)
	v_mov_b64_e32 v[136:137], v[156:157]
	global_load_dwordx2 v[156:157], v163, s[86:87] offset:64
	v_lshlrev_b32_e32 v144, 16, v136
	v_and_b32_e32 v136, 0xffff0000, v136
	v_mul_f32_e32 v136, 0xbfb8aa3b, v136
	v_exp_f32_e32 v136, v136
	v_mul_f32_e32 v144, 0xbfb8aa3b, v144
	v_exp_f32_e32 v144, v144
	v_add_f32_e32 v136, 1.0, v136
	v_rcp_f32_e32 v145, v136
	v_lshlrev_b32_e32 v136, 16, v137
	v_and_b32_e32 v137, 0xffff0000, v137
	v_mul_f32_e32 v136, 0xbfb8aa3b, v136
	v_mul_f32_e32 v137, 0xbfb8aa3b, v137
	v_exp_f32_e32 v136, v136
	v_exp_f32_e32 v137, v137
	v_add_f32_e32 v144, 1.0, v144
	v_rcp_f32_e32 v144, v144
	v_add_f32_e32 v136, 1.0, v136
	v_add_f32_e32 v137, 1.0, v137
	v_rcp_f32_e32 v136, v136
	v_rcp_f32_e32 v137, v137
	v_pk_mul_f32 v[144:145], v[114:115], v[144:145]
	v_pk_mul_f32 v[136:137], v[116:117], v[136:137]
	v_cvt_pk_bf16_f32 v144, v144, v145
	v_cvt_pk_bf16_f32 v145, v136, v137
	v_or_b32_e32 v136, 16, v141
	v_mul_u32_u24_e32 v136, 0x2a30, v136
	v_mov_b32_e32 v137, v1
	v_lshl_add_u64 v[136:137], s[16:17], 0, v[136:137]
	v_lshl_add_u64 v[136:137], v[136:137], 0, s[6:7]
	ds_write2_b64 v138, v[142:143], v[144:145] offset0:8 offset1:12
	v_lshl_add_u64 v[142:143], v[136:137], 0, v[130:131]
	s_waitcnt vmcnt(6)
	v_mov_b64_e32 v[142:143], v[160:161]
	global_load_dwordx2 v[160:161], v163, s[86:87] offset:96
	v_lshlrev_b32_e32 v144, 16, v142
	v_and_b32_e32 v142, 0xffff0000, v142
	v_mul_f32_e32 v142, 0xbfb8aa3b, v142
	v_exp_f32_e32 v142, v142
	v_mul_f32_e32 v144, 0xbfb8aa3b, v144
	v_exp_f32_e32 v144, v144
	v_add_f32_e32 v142, 1.0, v142
	v_rcp_f32_e32 v145, v142
	v_lshlrev_b32_e32 v142, 16, v143
	v_and_b32_e32 v143, 0xffff0000, v143
	v_mul_f32_e32 v142, 0xbfb8aa3b, v142
	v_mul_f32_e32 v143, 0xbfb8aa3b, v143
	v_exp_f32_e32 v142, v142
	v_exp_f32_e32 v143, v143
	v_add_f32_e32 v144, 1.0, v144
	v_rcp_f32_e32 v144, v144
	v_add_f32_e32 v142, 1.0, v142
	v_add_f32_e32 v143, 1.0, v143
	v_rcp_f32_e32 v142, v142
	v_rcp_f32_e32 v143, v143
	v_pk_mul_f32 v[144:145], v[110:111], v[144:145]
	v_pk_mul_f32 v[142:143], v[112:113], v[142:143]
	v_cvt_pk_bf16_f32 v144, v144, v145
	v_cvt_pk_bf16_f32 v145, v142, v143
	v_lshl_add_u64 v[142:143], v[136:137], 0, v[0:1]
	s_waitcnt vmcnt(6)
	v_mov_b64_e32 v[142:143], v[188:189]
	s_add_u32 s86, s86, 0x2a300
	s_addc_u32 s87, s87, 0
	global_load_dwordx2 v[188:189], v163, s[86:87]
	v_lshlrev_b32_e32 v146, 16, v142
	v_and_b32_e32 v142, 0xffff0000, v142
	v_mul_f32_e32 v142, 0xbfb8aa3b, v142
	v_exp_f32_e32 v142, v142
	v_mul_f32_e32 v146, 0xbfb8aa3b, v146
	v_exp_f32_e32 v146, v146
	v_add_f32_e32 v142, 1.0, v142
	v_rcp_f32_e32 v147, v142
	v_lshlrev_b32_e32 v142, 16, v143
	v_and_b32_e32 v143, 0xffff0000, v143
	v_mul_f32_e32 v142, 0xbfb8aa3b, v142
	v_mul_f32_e32 v143, 0xbfb8aa3b, v143
	v_exp_f32_e32 v142, v142
	v_exp_f32_e32 v143, v143
	v_add_f32_e32 v146, 1.0, v146
	v_rcp_f32_e32 v146, v146
	v_add_f32_e32 v142, 1.0, v142
	v_add_f32_e32 v143, 1.0, v143
	v_rcp_f32_e32 v142, v142
	v_rcp_f32_e32 v143, v143
	v_pk_mul_f32 v[146:147], v[106:107], v[146:147]
	v_pk_mul_f32 v[142:143], v[108:109], v[142:143]
	v_cvt_pk_bf16_f32 v146, v146, v147
	v_cvt_pk_bf16_f32 v147, v142, v143
	v_add_u32_e32 v142, 0x2000, v138
	ds_write2_b64 v142, v[144:145], v[146:147] offset0:32 offset1:36
	v_lshl_add_u64 v[144:145], v[136:137], 0, v[134:135]
	s_waitcnt vmcnt(6)
	v_mov_b64_e32 v[144:145], v[190:191]
	global_load_dwordx2 v[190:191], v163, s[86:87] offset:32
	v_lshl_add_u64 v[136:137], v[136:137], 0, v[132:133]
	s_waitcnt vmcnt(6)
; DI float bflo(unsigned u) { return __uint_as_float(u << 16); }
; DI float bfhi(unsigned u) { return __uint_as_float(u & 0xffff0000u); }
; DI float sigmoidf(float x) { return __builtin_amdgcn_rcpf(1.f + __expf(-x)); }
; template <class F>
; DI void gemm8_epi_staged(f32x4 (&acc)[8][4], int m0, int n0, bf16_t* L0, F f, bf16_t* dst, size_t ld, int nmax) {
;     ...
;       for (int i = 0; i < 8; ++i)
; #pragma unroll
;         for (int j = 0; j < 4; ++j) {
;           const int ml = i * 16 + (lane & 15);
;           const int nl = wn * 64 + j * 16 + (lane >> 4) * 4;
;           f32x4 a = acc[i][j];
;           f(m0 + half * 128 + ml, n0 + nl, a);
;           uint2 u;
;           u.x = pack2(a[0], a[1]);
;           u.y = pack2(a[2], a[3]);
;           *(uint2*)(L + ml * 264 + nl) = u;
;         }
; __global__ void __launch_bounds__(512, 2) mega(Params p) {
;     ...
;       gemm8_epi_staged(acc8, m0, n0, lds_all, [&](int m, int n, f32x4& a) {
;         uint2 ub = *(const uint2*)(z + (size_t)m * ZS + C_MB + n);
;         a[0] *= sigmoidf(bflo(ub.x)); a[1] *= sigmoidf(bfhi(ub.x));
;         a[2] *= sigmoidf(bflo(ub.y)); a[3] *= sigmoidf(bfhi(ub.y));
;       }, z + C_RK, ZS, 1024);
	v_mov_b64_e32 v[136:137], v[150:151]
	global_load_dwordx2 v[150:151], v163, s[86:87] offset:64
	v_lshlrev_b32_e32 v143, 16, v144
	v_mul_f32_e32 v143, 0xbfb8aa3b, v143
	v_exp_f32_e32 v143, v143
	s_nop 0
	v_add_f32_e32 v143, 1.0, v143
	v_rcp_f32_e32 v146, v143
	v_and_b32_e32 v143, 0xffff0000, v144
	v_mul_f32_e32 v143, 0xbfb8aa3b, v143
	v_exp_f32_e32 v143, v143
	s_nop 0
	v_add_f32_e32 v143, 1.0, v143
	v_rcp_f32_e32 v147, v143
	v_lshlrev_b32_e32 v143, 16, v145
	v_mul_f32_e32 v143, 0xbfb8aa3b, v143
	v_exp_f32_e32 v143, v143
	v_pk_mul_f32 v[146:147], v[102:103], v[146:147]
	v_add_f32_e32 v143, 1.0, v143
	v_rcp_f32_e32 v144, v143
	v_and_b32_e32 v143, 0xffff0000, v145
	v_mul_f32_e32 v143, 0xbfb8aa3b, v143
	v_exp_f32_e32 v143, v143
	v_cvt_pk_bf16_f32 v146, v146, v147
	v_add_f32_e32 v143, 1.0, v143
	v_rcp_f32_e32 v145, v143
	v_lshlrev_b32_e32 v143, 16, v136
	v_and_b32_e32 v136, 0xffff0000, v136
	v_mul_f32_e32 v136, 0xbfb8aa3b, v136
	v_exp_f32_e32 v136, v136
	v_pk_mul_f32 v[144:145], v[104:105], v[144:145]
	v_mul_f32_e32 v143, 0xbfb8aa3b, v143
	v_cvt_pk_bf16_f32 v147, v144, v145
	v_add_f32_e32 v136, 1.0, v136
	v_rcp_f32_e32 v145, v136
	v_lshlrev_b32_e32 v136, 16, v137
	v_and_b32_e32 v137, 0xffff0000, v137
	v_mul_f32_e32 v136, 0xbfb8aa3b, v136
	v_mul_f32_e32 v137, 0xbfb8aa3b, v137
	v_exp_f32_e32 v143, v143
	v_exp_f32_e32 v136, v136
	v_exp_f32_e32 v137, v137
	v_add_f32_e32 v143, 1.0, v143
	v_add_f32_e32 v136, 1.0, v136
	v_add_f32_e32 v137, 1.0, v137
	v_rcp_f32_e32 v144, v143
	v_rcp_f32_e32 v136, v136
	v_rcp_f32_e32 v137, v137
	v_pk_mul_f32 v[144:145], v[98:99], v[144:145]
	s_nop 0
	v_cvt_pk_bf16_f32 v144, v144, v145
	v_pk_mul_f32 v[136:137], v[100:101], v[136:137]
	s_nop 0
	v_cvt_pk_bf16_f32 v145, v136, v137
	v_or_b32_e32 v136, 32, v141
	v_mul_u32_u24_e32 v136, 0x2a30, v136
	v_mov_b32_e32 v137, v1
	v_lshl_add_u64 v[136:137], s[16:17], 0, v[136:137]
	v_lshl_add_u64 v[136:137], v[136:137], 0, s[6:7]
	ds_write2_b64 v142, v[146:147], v[144:145] offset0:40 offset1:44
	v_lshl_add_u64 v[142:143], v[136:137], 0, v[130:131]
	s_waitcnt vmcnt(6)
	v_mov_b64_e32 v[142:143], v[152:153]
	global_load_dwordx2 v[152:153], v163, s[86:87] offset:96
	v_lshlrev_b32_e32 v144, 16, v142
	v_and_b32_e32 v142, 0xffff0000, v142
	v_mul_f32_e32 v142, 0xbfb8aa3b, v142
	v_exp_f32_e32 v142, v142
	v_mul_f32_e32 v144, 0xbfb8aa3b, v144
	v_exp_f32_e32 v144, v144
	v_add_f32_e32 v142, 1.0, v142
	v_rcp_f32_e32 v145, v142
	v_lshlrev_b32_e32 v142, 16, v143
	v_and_b32_e32 v143, 0xffff0000, v143
	v_mul_f32_e32 v142, 0xbfb8aa3b, v142
	v_mul_f32_e32 v143, 0xbfb8aa3b, v143
	v_exp_f32_e32 v142, v142
	v_exp_f32_e32 v143, v143
	v_add_f32_e32 v144, 1.0, v144
	v_rcp_f32_e32 v144, v144
	v_add_f32_e32 v142, 1.0, v142
	v_add_f32_e32 v143, 1.0, v143
	v_rcp_f32_e32 v142, v142
	v_rcp_f32_e32 v143, v143
	v_pk_mul_f32 v[144:145], v[94:95], v[144:145]
	v_pk_mul_f32 v[142:143], v[96:97], v[142:143]
	v_cvt_pk_bf16_f32 v144, v144, v145
	v_cvt_pk_bf16_f32 v145, v142, v143
	v_lshl_add_u64 v[142:143], v[136:137], 0, v[0:1]
	s_waitcnt vmcnt(6)
	v_mov_b64_e32 v[142:143], v[154:155]
	s_add_u32 s86, s86, 0x2a300
	s_addc_u32 s87, s87, 0
	global_load_dwordx2 v[154:155], v163, s[86:87]
	v_lshlrev_b32_e32 v146, 16, v142
	v_and_b32_e32 v142, 0xffff0000, v142
	v_mul_f32_e32 v142, 0xbfb8aa3b, v142
	v_exp_f32_e32 v142, v142
	v_mul_f32_e32 v146, 0xbfb8aa3b, v146
	v_exp_f32_e32 v146, v146
	v_add_f32_e32 v142, 1.0, v142
	v_rcp_f32_e32 v147, v142
	v_lshlrev_b32_e32 v142, 16, v143
	v_and_b32_e32 v143, 0xffff0000, v143
	v_mul_f32_e32 v142, 0xbfb8aa3b, v142
	v_mul_f32_e32 v143, 0xbfb8aa3b, v143
	v_exp_f32_e32 v142, v142
	v_exp_f32_e32 v143, v143
	v_add_f32_e32 v146, 1.0, v146
	v_rcp_f32_e32 v146, v146
	v_add_f32_e32 v142, 1.0, v142
	v_add_f32_e32 v143, 1.0, v143
	v_rcp_f32_e32 v142, v142
	v_rcp_f32_e32 v143, v143
	v_pk_mul_f32 v[146:147], v[90:91], v[146:147]
	v_pk_mul_f32 v[142:143], v[92:93], v[142:143]
	v_cvt_pk_bf16_f32 v146, v146, v147
	v_cvt_pk_bf16_f32 v147, v142, v143
	v_lshl_add_u64 v[142:143], v[136:137], 0, v[134:135]
	s_waitcnt vmcnt(6)
	v_mov_b64_e32 v[142:143], v[156:157]
	global_load_dwordx2 v[156:157], v163, s[86:87] offset:32
	v_lshl_add_u64 v[136:137], v[136:137], 0, v[132:133]
	s_waitcnt vmcnt(6)
	v_mov_b64_e32 v[136:137], v[160:161]
	global_load_dwordx2 v[160:161], v163, s[86:87] offset:64
	ds_write2_b64 v148, v[144:145], v[146:147] offset0:64 offset1:68
	v_lshlrev_b32_e32 v144, 16, v142
	v_and_b32_e32 v142, 0xffff0000, v142
	v_mul_f32_e32 v142, 0xbfb8aa3b, v142
	v_exp_f32_e32 v142, v142
	v_mul_f32_e32 v144, 0xbfb8aa3b, v144
	v_exp_f32_e32 v144, v144
	v_add_f32_e32 v142, 1.0, v142
	v_rcp_f32_e32 v145, v142
	v_lshlrev_b32_e32 v142, 16, v143
	v_and_b32_e32 v143, 0xffff0000, v143
	v_mul_f32_e32 v142, 0xbfb8aa3b, v142
	v_mul_f32_e32 v143, 0xbfb8aa3b, v143
	v_exp_f32_e32 v142, v142
	v_exp_f32_e32 v143, v143
	v_add_f32_e32 v144, 1.0, v144
	v_rcp_f32_e32 v144, v144
	v_add_f32_e32 v142, 1.0, v142
	v_add_f32_e32 v143, 1.0, v143
	v_rcp_f32_e32 v142, v142
	v_rcp_f32_e32 v143, v143
	v_pk_mul_f32 v[144:145], v[86:87], v[144:145]
	v_pk_mul_f32 v[142:143], v[88:89], v[142:143]
	v_cvt_pk_bf16_f32 v144, v144, v145
	v_cvt_pk_bf16_f32 v145, v142, v143
	v_lshlrev_b32_e32 v142, 16, v136
	v_and_b32_e32 v136, 0xffff0000, v136
	v_mul_f32_e32 v136, 0xbfb8aa3b, v136
	v_exp_f32_e32 v136, v136
	v_mul_f32_e32 v142, 0xbfb8aa3b, v142
	v_exp_f32_e32 v142, v142
	v_add_f32_e32 v136, 1.0, v136
	v_rcp_f32_e32 v143, v136
	v_lshlrev_b32_e32 v136, 16, v137
	v_and_b32_e32 v137, 0xffff0000, v137
	v_mul_f32_e32 v136, 0xbfb8aa3b, v136
	v_mul_f32_e32 v137, 0xbfb8aa3b, v137
	v_exp_f32_e32 v136, v136
	v_exp_f32_e32 v137, v137
	v_add_f32_e32 v142, 1.0, v142
	v_rcp_f32_e32 v142, v142
	v_add_f32_e32 v136, 1.0, v136
	v_add_f32_e32 v137, 1.0, v137
	v_rcp_f32_e32 v136, v136
	v_rcp_f32_e32 v137, v137
	v_pk_mul_f32 v[142:143], v[82:83], v[142:143]
	v_pk_mul_f32 v[136:137], v[84:85], v[136:137]
	v_cvt_pk_bf16_f32 v142, v142, v143
	v_cvt_pk_bf16_f32 v143, v136, v137
	v_or_b32_e32 v136, 48, v141
	v_mul_u32_u24_e32 v136, 0x2a30, v136
	v_mov_b32_e32 v137, v1
	v_lshl_add_u64 v[136:137], s[16:17], 0, v[136:137]
	v_lshl_add_u64 v[136:137], v[136:137], 0, s[6:7]
	ds_write2_b64 v148, v[144:145], v[142:143] offset0:72 offset1:76
	v_lshl_add_u64 v[142:143], v[136:137], 0, v[130:131]
	s_waitcnt vmcnt(6)
; DI float bflo(unsigned u) { return __uint_as_float(u << 16); }
; DI float bfhi(unsigned u) { return __uint_as_float(u & 0xffff0000u); }
; DI float sigmoidf(float x) { return __builtin_amdgcn_rcpf(1.f + __expf(-x)); }
; template <class F>
; DI void gemm8_epi_staged(f32x4 (&acc)[8][4], int m0, int n0, bf16_t* L0, F f, bf16_t* dst, size_t ld, int nmax) {
;     ...
;       for (int i = 0; i < 8; ++i)
; #pragma unroll
;         for (int j = 0; j < 4; ++j) {
;           const int ml = i * 16 + (lane & 15);
;           const int nl = wn * 64 + j * 16 + (lane >> 4) * 4;
;           f32x4 a = acc[i][j];
;           f(m0 + half * 128 + ml, n0 + nl, a);
;           uint2 u;
;           u.x = pack2(a[0], a[1]);
;           u.y = pack2(a[2], a[3]);
;           *(uint2*)(L + ml * 264 + nl) = u;
;         }
; __global__ void __launch_bounds__(512, 2) mega(Params p) {
;     ...
;       gemm8_epi_staged(acc8, m0, n0, lds_all, [&](int m, int n, f32x4& a) {
;         uint2 ub = *(const uint2*)(z + (size_t)m * ZS + C_MB + n);
;         a[0] *= sigmoidf(bflo(ub.x)); a[1] *= sigmoidf(bfhi(ub.x));
;         a[2] *= sigmoidf(bflo(ub.y)); a[3] *= sigmoidf(bfhi(ub.y));
;       }, z + C_RK, ZS, 1024);
	v_mov_b64_e32 v[142:143], v[188:189]
	global_load_dwordx2 v[188:189], v163, s[86:87] offset:96
	v_add_u32_e32 v148, 0x6000, v138
	v_lshlrev_b32_e32 v144, 16, v142
	v_and_b32_e32 v142, 0xffff0000, v142
	v_mul_f32_e32 v142, 0xbfb8aa3b, v142
	v_exp_f32_e32 v142, v142
	v_mul_f32_e32 v144, 0xbfb8aa3b, v144
	v_exp_f32_e32 v144, v144
	v_add_f32_e32 v142, 1.0, v142
	v_rcp_f32_e32 v145, v142
	v_lshlrev_b32_e32 v142, 16, v143
	v_and_b32_e32 v143, 0xffff0000, v143
	v_mul_f32_e32 v142, 0xbfb8aa3b, v142
	v_mul_f32_e32 v143, 0xbfb8aa3b, v143
	v_exp_f32_e32 v142, v142
	v_exp_f32_e32 v143, v143
	v_add_f32_e32 v144, 1.0, v144
	v_rcp_f32_e32 v144, v144
	v_add_f32_e32 v142, 1.0, v142
	v_add_f32_e32 v143, 1.0, v143
	v_rcp_f32_e32 v142, v142
	v_rcp_f32_e32 v143, v143
	v_pk_mul_f32 v[144:145], v[78:79], v[144:145]
	v_pk_mul_f32 v[142:143], v[80:81], v[142:143]
	v_cvt_pk_bf16_f32 v144, v144, v145
	v_cvt_pk_bf16_f32 v145, v142, v143
	v_lshl_add_u64 v[142:143], v[136:137], 0, v[0:1]
	s_waitcnt vmcnt(6)
	v_mov_b64_e32 v[142:143], v[190:191]
	s_add_u32 s86, s86, 0x2a300
	s_addc_u32 s87, s87, 0
	global_load_dwordx2 v[190:191], v163, s[86:87]
	v_lshlrev_b32_e32 v146, 16, v142
	v_and_b32_e32 v142, 0xffff0000, v142
	v_mul_f32_e32 v142, 0xbfb8aa3b, v142
	v_exp_f32_e32 v142, v142
	v_mul_f32_e32 v146, 0xbfb8aa3b, v146
	v_exp_f32_e32 v146, v146
	v_add_f32_e32 v142, 1.0, v142
	v_rcp_f32_e32 v147, v142
	v_lshlrev_b32_e32 v142, 16, v143
	v_and_b32_e32 v143, 0xffff0000, v143
	v_mul_f32_e32 v142, 0xbfb8aa3b, v142
	v_mul_f32_e32 v143, 0xbfb8aa3b, v143
	v_exp_f32_e32 v142, v142
	v_exp_f32_e32 v143, v143
	v_add_f32_e32 v146, 1.0, v146
	v_rcp_f32_e32 v146, v146
	v_add_f32_e32 v142, 1.0, v142
	v_add_f32_e32 v143, 1.0, v143
	v_rcp_f32_e32 v142, v142
	v_rcp_f32_e32 v143, v143
	v_pk_mul_f32 v[146:147], v[74:75], v[146:147]
	v_pk_mul_f32 v[142:143], v[76:77], v[142:143]
	v_cvt_pk_bf16_f32 v146, v146, v147
	v_cvt_pk_bf16_f32 v147, v142, v143
	v_lshl_add_u64 v[142:143], v[136:137], 0, v[134:135]
	s_waitcnt vmcnt(6)
	v_mov_b64_e32 v[142:143], v[150:151]
	global_load_dwordx2 v[150:151], v163, s[86:87] offset:32
	v_lshl_add_u64 v[136:137], v[136:137], 0, v[132:133]
	s_waitcnt vmcnt(6)
	v_mov_b64_e32 v[136:137], v[152:153]
	global_load_dwordx2 v[152:153], v163, s[86:87] offset:64
	ds_write2_b64 v148, v[144:145], v[146:147] offset0:96 offset1:100
	v_lshlrev_b32_e32 v144, 16, v142
	v_and_b32_e32 v142, 0xffff0000, v142
	v_mul_f32_e32 v142, 0xbfb8aa3b, v142
	v_exp_f32_e32 v142, v142
	v_mul_f32_e32 v144, 0xbfb8aa3b, v144
	v_exp_f32_e32 v144, v144
	v_add_f32_e32 v142, 1.0, v142
	v_rcp_f32_e32 v145, v142
	v_lshlrev_b32_e32 v142, 16, v143
	v_and_b32_e32 v143, 0xffff0000, v143
	v_mul_f32_e32 v142, 0xbfb8aa3b, v142
	v_mul_f32_e32 v143, 0xbfb8aa3b, v143
	v_exp_f32_e32 v142, v142
	v_exp_f32_e32 v143, v143
	v_add_f32_e32 v144, 1.0, v144
	v_rcp_f32_e32 v144, v144
	v_add_f32_e32 v142, 1.0, v142
	v_add_f32_e32 v143, 1.0, v143
	v_rcp_f32_e32 v142, v142
	v_rcp_f32_e32 v143, v143
	v_pk_mul_f32 v[144:145], v[70:71], v[144:145]
	v_pk_mul_f32 v[142:143], v[72:73], v[142:143]
	v_cvt_pk_bf16_f32 v144, v144, v145
	v_cvt_pk_bf16_f32 v145, v142, v143
	v_lshlrev_b32_e32 v142, 16, v136
	v_and_b32_e32 v136, 0xffff0000, v136
	v_mul_f32_e32 v136, 0xbfb8aa3b, v136
	v_exp_f32_e32 v136, v136
	v_mul_f32_e32 v142, 0xbfb8aa3b, v142
	v_exp_f32_e32 v142, v142
	v_add_f32_e32 v136, 1.0, v136
	v_rcp_f32_e32 v143, v136
	v_lshlrev_b32_e32 v136, 16, v137
	v_and_b32_e32 v137, 0xffff0000, v137
	v_mul_f32_e32 v136, 0xbfb8aa3b, v136
	v_mul_f32_e32 v137, 0xbfb8aa3b, v137
	v_exp_f32_e32 v136, v136
	v_exp_f32_e32 v137, v137
	v_add_f32_e32 v142, 1.0, v142
	v_rcp_f32_e32 v142, v142
	v_add_f32_e32 v136, 1.0, v136
	v_add_f32_e32 v137, 1.0, v137
	v_rcp_f32_e32 v136, v136
	v_rcp_f32_e32 v137, v137
	v_pk_mul_f32 v[142:143], v[66:67], v[142:143]
	v_pk_mul_f32 v[136:137], v[68:69], v[136:137]
	v_cvt_pk_bf16_f32 v142, v142, v143
	v_cvt_pk_bf16_f32 v143, v136, v137
	v_or_b32_e32 v136, 64, v141
	v_mul_u32_u24_e32 v136, 0x2a30, v136
	v_mov_b32_e32 v137, v1
	v_lshl_add_u64 v[136:137], s[16:17], 0, v[136:137]
	v_lshl_add_u64 v[136:137], v[136:137], 0, s[6:7]
	ds_write2_b64 v148, v[144:145], v[142:143] offset0:104 offset1:108
	v_lshl_add_u64 v[142:143], v[136:137], 0, v[130:131]
	s_waitcnt vmcnt(6)
	v_mov_b64_e32 v[142:143], v[154:155]
	global_load_dwordx2 v[154:155], v163, s[86:87] offset:96
	v_add_u32_e32 v148, 0x8000, v138
	v_lshlrev_b32_e32 v144, 16, v142
	v_and_b32_e32 v142, 0xffff0000, v142
	v_mul_f32_e32 v142, 0xbfb8aa3b, v142
	v_exp_f32_e32 v142, v142
	v_mul_f32_e32 v144, 0xbfb8aa3b, v144
	v_exp_f32_e32 v144, v144
	v_add_f32_e32 v142, 1.0, v142
	v_rcp_f32_e32 v145, v142
	v_lshlrev_b32_e32 v142, 16, v143
	v_and_b32_e32 v143, 0xffff0000, v143
	v_mul_f32_e32 v142, 0xbfb8aa3b, v142
	v_mul_f32_e32 v143, 0xbfb8aa3b, v143
	v_exp_f32_e32 v142, v142
	v_exp_f32_e32 v143, v143
	v_add_f32_e32 v144, 1.0, v144
	v_rcp_f32_e32 v144, v144
	v_add_f32_e32 v142, 1.0, v142
	v_add_f32_e32 v143, 1.0, v143
	v_rcp_f32_e32 v142, v142
	v_rcp_f32_e32 v143, v143
	v_pk_mul_f32 v[144:145], v[62:63], v[144:145]
	v_pk_mul_f32 v[142:143], v[64:65], v[142:143]
	v_cvt_pk_bf16_f32 v144, v144, v145
	v_cvt_pk_bf16_f32 v145, v142, v143
	v_lshl_add_u64 v[142:143], v[136:137], 0, v[0:1]
	s_waitcnt vmcnt(6)
; DI float bflo(unsigned u) { return __uint_as_float(u << 16); }
; DI float bfhi(unsigned u) { return __uint_as_float(u & 0xffff0000u); }
; DI float sigmoidf(float x) { return __builtin_amdgcn_rcpf(1.f + __expf(-x)); }
; template <class F>
; DI void gemm8_epi_staged(f32x4 (&acc)[8][4], int m0, int n0, bf16_t* L0, F f, bf16_t* dst, size_t ld, int nmax) {
;     ...
;       for (int i = 0; i < 8; ++i)
; #pragma unroll
;         for (int j = 0; j < 4; ++j) {
;           const int ml = i * 16 + (lane & 15);
;           const int nl = wn * 64 + j * 16 + (lane >> 4) * 4;
;           f32x4 a = acc[i][j];
;           f(m0 + half * 128 + ml, n0 + nl, a);
;           uint2 u;
;           u.x = pack2(a[0], a[1]);
;           u.y = pack2(a[2], a[3]);
;           *(uint2*)(L + ml * 264 + nl) = u;
;         }
; __global__ void __launch_bounds__(512, 2) mega(Params p) {
;     ...
;       gemm8_epi_staged(acc8, m0, n0, lds_all, [&](int m, int n, f32x4& a) {
;         uint2 ub = *(const uint2*)(z + (size_t)m * ZS + C_MB + n);
;         a[0] *= sigmoidf(bflo(ub.x)); a[1] *= sigmoidf(bfhi(ub.x));
;         a[2] *= sigmoidf(bflo(ub.y)); a[3] *= sigmoidf(bfhi(ub.y));
;       }, z + C_RK, ZS, 1024);
	v_mov_b64_e32 v[142:143], v[156:157]
	s_add_u32 s86, s86, 0x2a300
	s_addc_u32 s87, s87, 0
	global_load_dwordx2 v[156:157], v163, s[86:87]
	v_lshlrev_b32_e32 v146, 16, v142
	v_and_b32_e32 v142, 0xffff0000, v142
	v_mul_f32_e32 v142, 0xbfb8aa3b, v142
	v_exp_f32_e32 v142, v142
	v_mul_f32_e32 v146, 0xbfb8aa3b, v146
	v_exp_f32_e32 v146, v146
	v_add_f32_e32 v142, 1.0, v142
	v_rcp_f32_e32 v147, v142
	v_lshlrev_b32_e32 v142, 16, v143
	v_and_b32_e32 v143, 0xffff0000, v143
	v_mul_f32_e32 v142, 0xbfb8aa3b, v142
	v_mul_f32_e32 v143, 0xbfb8aa3b, v143
	v_exp_f32_e32 v142, v142
	v_exp_f32_e32 v143, v143
	v_add_f32_e32 v146, 1.0, v146
	v_rcp_f32_e32 v146, v146
	v_add_f32_e32 v142, 1.0, v142
	v_add_f32_e32 v143, 1.0, v143
	v_rcp_f32_e32 v142, v142
	v_rcp_f32_e32 v143, v143
	v_pk_mul_f32 v[146:147], v[58:59], v[146:147]
	v_pk_mul_f32 v[142:143], v[60:61], v[142:143]
	v_cvt_pk_bf16_f32 v146, v146, v147
	v_cvt_pk_bf16_f32 v147, v142, v143
	v_lshl_add_u64 v[142:143], v[136:137], 0, v[134:135]
	s_waitcnt vmcnt(6)
	v_mov_b64_e32 v[142:143], v[160:161]
	global_load_dwordx2 v[160:161], v163, s[86:87] offset:32
	v_lshl_add_u64 v[136:137], v[136:137], 0, v[132:133]
	s_waitcnt vmcnt(6)
	v_mov_b64_e32 v[136:137], v[188:189]
	global_load_dwordx2 v[188:189], v163, s[86:87] offset:64
	ds_write2_b64 v148, v[144:145], v[146:147] offset0:128 offset1:132
	v_lshlrev_b32_e32 v144, 16, v142
	v_and_b32_e32 v142, 0xffff0000, v142
	v_mul_f32_e32 v142, 0xbfb8aa3b, v142
	v_exp_f32_e32 v142, v142
	v_mul_f32_e32 v144, 0xbfb8aa3b, v144
	v_exp_f32_e32 v144, v144
	v_add_f32_e32 v142, 1.0, v142
	v_rcp_f32_e32 v145, v142
	v_lshlrev_b32_e32 v142, 16, v143
	v_and_b32_e32 v143, 0xffff0000, v143
	v_mul_f32_e32 v142, 0xbfb8aa3b, v142
	v_mul_f32_e32 v143, 0xbfb8aa3b, v143
	v_exp_f32_e32 v142, v142
	v_exp_f32_e32 v143, v143
	v_add_f32_e32 v144, 1.0, v144
	v_rcp_f32_e32 v144, v144
	v_add_f32_e32 v142, 1.0, v142
	v_add_f32_e32 v143, 1.0, v143
	v_rcp_f32_e32 v142, v142
	v_rcp_f32_e32 v143, v143
	v_pk_mul_f32 v[144:145], v[54:55], v[144:145]
	v_pk_mul_f32 v[142:143], v[56:57], v[142:143]
	v_cvt_pk_bf16_f32 v144, v144, v145
	v_cvt_pk_bf16_f32 v145, v142, v143
	v_lshlrev_b32_e32 v142, 16, v136
	v_and_b32_e32 v136, 0xffff0000, v136
	v_mul_f32_e32 v136, 0xbfb8aa3b, v136
	v_exp_f32_e32 v136, v136
	v_mul_f32_e32 v142, 0xbfb8aa3b, v142
	v_exp_f32_e32 v142, v142
	v_add_f32_e32 v136, 1.0, v136
	v_rcp_f32_e32 v143, v136
	v_lshlrev_b32_e32 v136, 16, v137
	v_and_b32_e32 v137, 0xffff0000, v137
	v_mul_f32_e32 v136, 0xbfb8aa3b, v136
	v_mul_f32_e32 v137, 0xbfb8aa3b, v137
	v_exp_f32_e32 v136, v136
	v_exp_f32_e32 v137, v137
	v_add_f32_e32 v142, 1.0, v142
	v_rcp_f32_e32 v142, v142
	v_add_f32_e32 v136, 1.0, v136
	v_add_f32_e32 v137, 1.0, v137
	v_rcp_f32_e32 v136, v136
	v_rcp_f32_e32 v137, v137
	v_pk_mul_f32 v[142:143], v[50:51], v[142:143]
	v_pk_mul_f32 v[136:137], v[52:53], v[136:137]
	v_cvt_pk_bf16_f32 v142, v142, v143
	v_cvt_pk_bf16_f32 v143, v136, v137
	v_or_b32_e32 v136, 0x50, v141
	v_mul_u32_u24_e32 v136, 0x2a30, v136
	v_mov_b32_e32 v137, v1
	v_lshl_add_u64 v[136:137], s[16:17], 0, v[136:137]
	v_lshl_add_u64 v[136:137], v[136:137], 0, s[6:7]
	ds_write2_b64 v148, v[144:145], v[142:143] offset0:136 offset1:140
	v_lshl_add_u64 v[142:143], v[136:137], 0, v[130:131]
	s_waitcnt vmcnt(6)
	v_mov_b64_e32 v[142:143], v[190:191]
	global_load_dwordx2 v[190:191], v163, s[86:87] offset:96
	v_add_u32_e32 v148, 0xa000, v138
	v_lshlrev_b32_e32 v144, 16, v142
	v_and_b32_e32 v142, 0xffff0000, v142
	v_mul_f32_e32 v142, 0xbfb8aa3b, v142
	v_exp_f32_e32 v142, v142
	v_mul_f32_e32 v144, 0xbfb8aa3b, v144
	v_exp_f32_e32 v144, v144
	v_add_f32_e32 v142, 1.0, v142
	v_rcp_f32_e32 v145, v142
	v_lshlrev_b32_e32 v142, 16, v143
	v_and_b32_e32 v143, 0xffff0000, v143
	v_mul_f32_e32 v142, 0xbfb8aa3b, v142
	v_mul_f32_e32 v143, 0xbfb8aa3b, v143
	v_exp_f32_e32 v142, v142
	v_exp_f32_e32 v143, v143
	v_add_f32_e32 v144, 1.0, v144
	v_rcp_f32_e32 v144, v144
	v_add_f32_e32 v142, 1.0, v142
	v_add_f32_e32 v143, 1.0, v143
	v_rcp_f32_e32 v142, v142
	v_rcp_f32_e32 v143, v143
	v_pk_mul_f32 v[144:145], v[46:47], v[144:145]
	v_pk_mul_f32 v[142:143], v[48:49], v[142:143]
	v_cvt_pk_bf16_f32 v144, v144, v145
	v_cvt_pk_bf16_f32 v145, v142, v143
	v_lshl_add_u64 v[142:143], v[136:137], 0, v[0:1]
	s_waitcnt vmcnt(6)
	v_mov_b64_e32 v[142:143], v[150:151]
	s_add_u32 s86, s86, 0x2a300
	s_addc_u32 s87, s87, 0
	global_load_dwordx2 v[150:151], v163, s[86:87]
	v_lshlrev_b32_e32 v146, 16, v142
	v_and_b32_e32 v142, 0xffff0000, v142
	v_mul_f32_e32 v142, 0xbfb8aa3b, v142
	v_exp_f32_e32 v142, v142
	v_mul_f32_e32 v146, 0xbfb8aa3b, v146
	v_exp_f32_e32 v146, v146
	v_add_f32_e32 v142, 1.0, v142
	v_rcp_f32_e32 v147, v142
	v_lshlrev_b32_e32 v142, 16, v143
	v_and_b32_e32 v143, 0xffff0000, v143
	v_mul_f32_e32 v142, 0xbfb8aa3b, v142
	v_mul_f32_e32 v143, 0xbfb8aa3b, v143
	v_exp_f32_e32 v142, v142
	v_exp_f32_e32 v143, v143
	v_add_f32_e32 v146, 1.0, v146
	v_rcp_f32_e32 v146, v146
	v_add_f32_e32 v142, 1.0, v142
	v_add_f32_e32 v143, 1.0, v143
	v_rcp_f32_e32 v142, v142
	v_rcp_f32_e32 v143, v143
	v_pk_mul_f32 v[146:147], v[42:43], v[146:147]
	v_pk_mul_f32 v[142:143], v[44:45], v[142:143]
	v_cvt_pk_bf16_f32 v146, v146, v147
	v_cvt_pk_bf16_f32 v147, v142, v143
	v_lshl_add_u64 v[142:143], v[136:137], 0, v[134:135]
	s_waitcnt vmcnt(6)
	v_mov_b64_e32 v[142:143], v[152:153]
	global_load_dwordx2 v[152:153], v163, s[86:87] offset:64
	v_lshl_add_u64 v[136:137], v[136:137], 0, v[132:133]
	s_waitcnt vmcnt(6)
; DI float bflo(unsigned u) { return __uint_as_float(u << 16); }
; DI float bfhi(unsigned u) { return __uint_as_float(u & 0xffff0000u); }
; DI float sigmoidf(float x) { return __builtin_amdgcn_rcpf(1.f + __expf(-x)); }
; template <class F>
; DI void gemm8_epi_staged(f32x4 (&acc)[8][4], int m0, int n0, bf16_t* L0, F f, bf16_t* dst, size_t ld, int nmax) {
;     ...
;       for (int i = 0; i < 8; ++i)
; #pragma unroll
;         for (int j = 0; j < 4; ++j) {
;           const int ml = i * 16 + (lane & 15);
;           const int nl = wn * 64 + j * 16 + (lane >> 4) * 4;
;           f32x4 a = acc[i][j];
;           f(m0 + half * 128 + ml, n0 + nl, a);
;           uint2 u;
;           u.x = pack2(a[0], a[1]);
;           u.y = pack2(a[2], a[3]);
;           *(uint2*)(L + ml * 264 + nl) = u;
;         }
; __global__ void __launch_bounds__(512, 2) mega(Params p) {
;     ...
;       gemm8_epi_staged(acc8, m0, n0, lds_all, [&](int m, int n, f32x4& a) {
;         uint2 ub = *(const uint2*)(z + (size_t)m * ZS + C_MB + n);
;         a[0] *= sigmoidf(bflo(ub.x)); a[1] *= sigmoidf(bfhi(ub.x));
;         a[2] *= sigmoidf(bflo(ub.y)); a[3] *= sigmoidf(bfhi(ub.y));
;       }, z + C_RK, ZS, 1024);
	v_mov_b64_e32 v[136:137], v[154:155]
	global_load_dwordx2 v[154:155], v163, s[86:87] offset:96
	ds_write2_b64 v148, v[144:145], v[146:147] offset0:160 offset1:164
	v_lshlrev_b32_e32 v144, 16, v142
	v_and_b32_e32 v142, 0xffff0000, v142
	v_mul_f32_e32 v142, 0xbfb8aa3b, v142
	v_exp_f32_e32 v142, v142
	v_mul_f32_e32 v144, 0xbfb8aa3b, v144
	v_exp_f32_e32 v144, v144
	v_add_f32_e32 v142, 1.0, v142
	v_rcp_f32_e32 v145, v142
	v_lshlrev_b32_e32 v142, 16, v143
	v_and_b32_e32 v143, 0xffff0000, v143
	v_mul_f32_e32 v142, 0xbfb8aa3b, v142
	v_mul_f32_e32 v143, 0xbfb8aa3b, v143
	v_exp_f32_e32 v142, v142
	v_exp_f32_e32 v143, v143
	v_add_f32_e32 v144, 1.0, v144
	v_rcp_f32_e32 v144, v144
	v_add_f32_e32 v142, 1.0, v142
	v_add_f32_e32 v143, 1.0, v143
	v_rcp_f32_e32 v142, v142
	v_rcp_f32_e32 v143, v143
	v_pk_mul_f32 v[144:145], v[38:39], v[144:145]
	v_pk_mul_f32 v[142:143], v[40:41], v[142:143]
	v_cvt_pk_bf16_f32 v144, v144, v145
	v_cvt_pk_bf16_f32 v145, v142, v143
	v_lshlrev_b32_e32 v142, 16, v136
	v_and_b32_e32 v136, 0xffff0000, v136
	v_mul_f32_e32 v136, 0xbfb8aa3b, v136
	v_exp_f32_e32 v136, v136
	v_mul_f32_e32 v142, 0xbfb8aa3b, v142
	v_exp_f32_e32 v142, v142
	v_add_f32_e32 v136, 1.0, v136
	v_rcp_f32_e32 v143, v136
	v_lshlrev_b32_e32 v136, 16, v137
	v_and_b32_e32 v137, 0xffff0000, v137
	v_mul_f32_e32 v136, 0xbfb8aa3b, v136
	v_mul_f32_e32 v137, 0xbfb8aa3b, v137
	v_exp_f32_e32 v136, v136
	v_exp_f32_e32 v137, v137
	v_add_f32_e32 v142, 1.0, v142
	v_rcp_f32_e32 v142, v142
	v_add_f32_e32 v136, 1.0, v136
	v_add_f32_e32 v137, 1.0, v137
	v_rcp_f32_e32 v136, v136
	v_rcp_f32_e32 v137, v137
	v_pk_mul_f32 v[142:143], v[34:35], v[142:143]
	v_pk_mul_f32 v[136:137], v[36:37], v[136:137]
	v_cvt_pk_bf16_f32 v142, v142, v143
	v_cvt_pk_bf16_f32 v143, v136, v137
	v_or_b32_e32 v136, 0x60, v141
	v_mul_u32_u24_e32 v136, 0x2a30, v136
	v_mov_b32_e32 v137, v1
	v_lshl_add_u64 v[136:137], s[16:17], 0, v[136:137]
	v_lshl_add_u64 v[136:137], v[136:137], 0, s[6:7]
	ds_write2_b64 v148, v[144:145], v[142:143] offset0:168 offset1:172
	v_lshl_add_u64 v[142:143], v[136:137], 0, v[130:131]
	s_waitcnt vmcnt(6)
	v_mov_b64_e32 v[142:143], v[156:157]
	global_load_dwordx2 v[156:157], v163, s[86:87] offset:32
	v_add_u32_e32 v148, 0xc000, v138
	v_lshlrev_b32_e32 v144, 16, v142
	v_and_b32_e32 v142, 0xffff0000, v142
	v_mul_f32_e32 v142, 0xbfb8aa3b, v142
	v_exp_f32_e32 v142, v142
	v_mul_f32_e32 v144, 0xbfb8aa3b, v144
	v_exp_f32_e32 v144, v144
	v_add_f32_e32 v142, 1.0, v142
	v_rcp_f32_e32 v145, v142
	v_lshlrev_b32_e32 v142, 16, v143
	v_and_b32_e32 v143, 0xffff0000, v143
	v_mul_f32_e32 v142, 0xbfb8aa3b, v142
	v_mul_f32_e32 v143, 0xbfb8aa3b, v143
	v_exp_f32_e32 v142, v142
	v_exp_f32_e32 v143, v143
	v_add_f32_e32 v144, 1.0, v144
	v_rcp_f32_e32 v144, v144
	v_add_f32_e32 v142, 1.0, v142
	v_add_f32_e32 v143, 1.0, v143
	v_rcp_f32_e32 v142, v142
	v_rcp_f32_e32 v143, v143
	v_pk_mul_f32 v[144:145], v[30:31], v[144:145]
	v_pk_mul_f32 v[142:143], v[32:33], v[142:143]
	v_cvt_pk_bf16_f32 v144, v144, v145
	v_cvt_pk_bf16_f32 v145, v142, v143
	v_lshl_add_u64 v[142:143], v[136:137], 0, v[0:1]
	s_waitcnt vmcnt(6)
	v_mov_b64_e32 v[142:143], v[160:161]
	v_lshlrev_b32_e32 v146, 16, v142
	v_and_b32_e32 v142, 0xffff0000, v142
	v_mul_f32_e32 v142, 0xbfb8aa3b, v142
	v_exp_f32_e32 v142, v142
	v_mul_f32_e32 v146, 0xbfb8aa3b, v146
	v_exp_f32_e32 v146, v146
	v_add_f32_e32 v142, 1.0, v142
	v_rcp_f32_e32 v147, v142
	v_lshlrev_b32_e32 v142, 16, v143
	v_and_b32_e32 v143, 0xffff0000, v143
	v_mul_f32_e32 v142, 0xbfb8aa3b, v142
	v_mul_f32_e32 v143, 0xbfb8aa3b, v143
	v_exp_f32_e32 v142, v142
	v_exp_f32_e32 v143, v143
	v_add_f32_e32 v146, 1.0, v146
	v_rcp_f32_e32 v146, v146
	v_add_f32_e32 v142, 1.0, v142
	v_add_f32_e32 v143, 1.0, v143
	v_rcp_f32_e32 v142, v142
	v_rcp_f32_e32 v143, v143
	v_pk_mul_f32 v[146:147], v[26:27], v[146:147]
	v_pk_mul_f32 v[142:143], v[28:29], v[142:143]
	v_cvt_pk_bf16_f32 v146, v146, v147
	v_cvt_pk_bf16_f32 v147, v142, v143
	v_lshl_add_u64 v[142:143], v[136:137], 0, v[134:135]
	s_waitcnt vmcnt(5)
	v_mov_b64_e32 v[142:143], v[188:189]
	v_lshl_add_u64 v[136:137], v[136:137], 0, v[132:133]
	s_waitcnt vmcnt(4)
; DI float bflo(unsigned u) { return __uint_as_float(u << 16); }
; DI float bfhi(unsigned u) { return __uint_as_float(u & 0xffff0000u); }
; DI float sigmoidf(float x) { return __builtin_amdgcn_rcpf(1.f + __expf(-x)); }
; template <class F>
; DI void gemm8_epi_staged(f32x4 (&acc)[8][4], int m0, int n0, bf16_t* L0, F f, bf16_t* dst, size_t ld, int nmax) {
;     ...
;       for (int i = 0; i < 8; ++i)
; #pragma unroll
;         for (int j = 0; j < 4; ++j) {
;           const int ml = i * 16 + (lane & 15);
;           const int nl = wn * 64 + j * 16 + (lane >> 4) * 4;
;           f32x4 a = acc[i][j];
;           f(m0 + half * 128 + ml, n0 + nl, a);
;           uint2 u;
;           u.x = pack2(a[0], a[1]);
;           u.y = pack2(a[2], a[3]);
;           *(uint2*)(L + ml * 264 + nl) = u;
;         }
; __global__ void __launch_bounds__(512, 2) mega(Params p) {
;     ...
;       gemm8_epi_staged(acc8, m0, n0, lds_all, [&](int m, int n, f32x4& a) {
;         uint2 ub = *(const uint2*)(z + (size_t)m * ZS + C_MB + n);
;         a[0] *= sigmoidf(bflo(ub.x)); a[1] *= sigmoidf(bfhi(ub.x));
;         a[2] *= sigmoidf(bflo(ub.y)); a[3] *= sigmoidf(bfhi(ub.y));
;       }, z + C_RK, ZS, 1024);
	v_mov_b64_e32 v[136:137], v[190:191]
	ds_write2_b64 v148, v[144:145], v[146:147] offset0:192 offset1:196
	v_lshlrev_b32_e32 v144, 16, v142
	v_and_b32_e32 v142, 0xffff0000, v142
	v_mul_f32_e32 v142, 0xbfb8aa3b, v142
	v_exp_f32_e32 v142, v142
	v_mul_f32_e32 v144, 0xbfb8aa3b, v144
	v_exp_f32_e32 v144, v144
	v_add_f32_e32 v142, 1.0, v142
	v_rcp_f32_e32 v145, v142
	v_lshlrev_b32_e32 v142, 16, v143
	v_and_b32_e32 v143, 0xffff0000, v143
	v_mul_f32_e32 v142, 0xbfb8aa3b, v142
	v_mul_f32_e32 v143, 0xbfb8aa3b, v143
	v_exp_f32_e32 v142, v142
	v_exp_f32_e32 v143, v143
	v_add_f32_e32 v144, 1.0, v144
	v_rcp_f32_e32 v144, v144
	v_add_f32_e32 v142, 1.0, v142
	v_add_f32_e32 v143, 1.0, v143
	v_rcp_f32_e32 v142, v142
	v_rcp_f32_e32 v143, v143
	v_pk_mul_f32 v[144:145], v[22:23], v[144:145]
	v_pk_mul_f32 v[142:143], v[24:25], v[142:143]
	v_cvt_pk_bf16_f32 v144, v144, v145
	v_cvt_pk_bf16_f32 v145, v142, v143
	v_lshlrev_b32_e32 v142, 16, v136
	v_and_b32_e32 v136, 0xffff0000, v136
	v_mul_f32_e32 v136, 0xbfb8aa3b, v136
	v_exp_f32_e32 v136, v136
	v_mul_f32_e32 v142, 0xbfb8aa3b, v142
	v_exp_f32_e32 v142, v142
	v_add_f32_e32 v136, 1.0, v136
	v_rcp_f32_e32 v143, v136
	v_lshlrev_b32_e32 v136, 16, v137
	v_and_b32_e32 v137, 0xffff0000, v137
	v_mul_f32_e32 v136, 0xbfb8aa3b, v136
	v_mul_f32_e32 v137, 0xbfb8aa3b, v137
	v_exp_f32_e32 v136, v136
	v_exp_f32_e32 v137, v137
	v_add_f32_e32 v142, 1.0, v142
	v_rcp_f32_e32 v142, v142
	v_add_f32_e32 v136, 1.0, v136
	v_add_f32_e32 v137, 1.0, v137
	v_rcp_f32_e32 v136, v136
	v_rcp_f32_e32 v137, v137
	v_pk_mul_f32 v[142:143], v[18:19], v[142:143]
	v_pk_mul_f32 v[136:137], v[20:21], v[136:137]
	v_cvt_pk_bf16_f32 v142, v142, v143
	v_cvt_pk_bf16_f32 v143, v136, v137
	v_or_b32_e32 v136, 0x70, v141
	v_mul_u32_u24_e32 v136, 0x2a30, v136
	v_mov_b32_e32 v137, v1
	v_lshl_add_u64 v[136:137], s[16:17], 0, v[136:137]
	v_lshl_add_u64 v[136:137], v[136:137], 0, s[6:7]
	ds_write2_b64 v148, v[144:145], v[142:143] offset0:200 offset1:204
	v_lshl_add_u64 v[142:143], v[136:137], 0, v[130:131]
	s_waitcnt vmcnt(3)
	v_mov_b64_e32 v[142:143], v[150:151]
	v_lshl_add_u64 v[134:135], v[136:137], 0, v[134:135]
	s_waitcnt vmcnt(2)
	v_mov_b64_e32 v[134:135], v[152:153]
	v_lshl_add_u64 v[132:133], v[136:137], 0, v[132:133]
	s_waitcnt vmcnt(1)
	v_mov_b64_e32 v[132:133], v[154:155]
	v_lshlrev_b32_e32 v131, 16, v142
	v_mul_f32_e32 v131, 0xbfb8aa3b, v131
	v_exp_f32_e32 v131, v131
	s_nop 0
	v_add_f32_e32 v131, 1.0, v131
	v_rcp_f32_e32 v144, v131
	v_and_b32_e32 v131, 0xffff0000, v142
	v_mul_f32_e32 v131, 0xbfb8aa3b, v131
	v_exp_f32_e32 v131, v131
	s_nop 0
	v_add_f32_e32 v131, 1.0, v131
	v_rcp_f32_e32 v145, v131
	v_lshlrev_b32_e32 v131, 16, v143
	v_mul_f32_e32 v131, 0xbfb8aa3b, v131
	v_exp_f32_e32 v131, v131
	v_pk_mul_f32 v[144:145], v[14:15], v[144:145]
	v_add_f32_e32 v131, 1.0, v131
	v_rcp_f32_e32 v142, v131
	v_and_b32_e32 v131, 0xffff0000, v143
	v_mul_f32_e32 v131, 0xbfb8aa3b, v131
	v_exp_f32_e32 v131, v131
	v_cvt_pk_bf16_f32 v144, v144, v145
	v_add_f32_e32 v131, 1.0, v131
	v_rcp_f32_e32 v143, v131
	v_lshlrev_b32_e32 v131, 16, v134
	v_mul_f32_e32 v131, 0xbfb8aa3b, v131
	v_exp_f32_e32 v131, v131
	v_pk_mul_f32 v[142:143], v[16:17], v[142:143]
	v_add_f32_e32 v131, 1.0, v131
	v_cvt_pk_bf16_f32 v145, v142, v143
	v_lshl_add_u64 v[142:143], v[136:137], 0, v[0:1]
	s_waitcnt vmcnt(0)
	v_mov_b64_e32 v[142:143], v[156:157]
	v_lshlrev_b32_e32 v0, 16, v142
	v_mul_f32_e32 v0, 0xbfb8aa3b, v0
	v_exp_f32_e32 v0, v0
	s_nop 0
	v_add_f32_e32 v0, 1.0, v0
	v_rcp_f32_e32 v146, v0
	v_and_b32_e32 v0, 0xffff0000, v142
	v_mul_f32_e32 v0, 0xbfb8aa3b, v0
	v_exp_f32_e32 v0, v0
	s_nop 0
	v_add_f32_e32 v0, 1.0, v0
	v_rcp_f32_e32 v147, v0
	v_lshlrev_b32_e32 v0, 16, v143
	v_mul_f32_e32 v0, 0xbfb8aa3b, v0
	v_exp_f32_e32 v0, v0
	v_pk_mul_f32 v[146:147], v[10:11], v[146:147]
	v_add_f32_e32 v0, 1.0, v0
	v_rcp_f32_e32 v142, v0
	v_and_b32_e32 v0, 0xffff0000, v143
	v_mul_f32_e32 v0, 0xbfb8aa3b, v0
	v_exp_f32_e32 v0, v0
	v_cvt_pk_bf16_f32 v146, v146, v147
	v_add_f32_e32 v0, 1.0, v0
	v_rcp_f32_e32 v143, v0
	v_add_u32_e32 v0, 0xe000, v138
	v_pk_mul_f32 v[142:143], v[12:13], v[142:143]
	s_nop 0
	v_cvt_pk_bf16_f32 v147, v142, v143
	v_rcp_f32_e32 v142, v131
	v_and_b32_e32 v131, 0xffff0000, v134
	v_mul_f32_e32 v131, 0xbfb8aa3b, v131
	v_exp_f32_e32 v131, v131
	ds_write2_b64 v0, v[144:145], v[146:147] offset0:224 offset1:228
	v_add_f32_e32 v131, 1.0, v131
	v_rcp_f32_e32 v143, v131
	v_lshlrev_b32_e32 v131, 16, v135
	v_mul_f32_e32 v131, 0xbfb8aa3b, v131
	v_exp_f32_e32 v131, v131
	v_pk_mul_f32 v[142:143], v[6:7], v[142:143]
	v_add_f32_e32 v131, 1.0, v131
	v_rcp_f32_e32 v134, v131
	v_and_b32_e32 v131, 0xffff0000, v135
	v_mul_f32_e32 v131, 0xbfb8aa3b, v131
	v_exp_f32_e32 v131, v131
	s_nop 0
	v_add_f32_e32 v131, 1.0, v131
	v_rcp_f32_e32 v135, v131
	v_lshlrev_b32_e32 v131, 16, v132
	v_mul_f32_e32 v131, 0xbfb8aa3b, v131
	v_exp_f32_e32 v131, v131
	v_pk_mul_f32 v[144:145], v[8:9], v[134:135]
	v_cvt_pk_bf16_f32 v134, v142, v143
	v_cvt_pk_bf16_f32 v135, v144, v145
	v_add_f32_e32 v131, 1.0, v131
	v_rcp_f32_e32 v136, v131
	v_and_b32_e32 v131, 0xffff0000, v132
	v_mul_f32_e32 v131, 0xbfb8aa3b, v131
	v_exp_f32_e32 v131, v131
	s_nop 0
	v_add_f32_e32 v131, 1.0, v131
	v_rcp_f32_e32 v137, v131
	v_lshlrev_b32_e32 v131, 16, v133
	v_mul_f32_e32 v131, 0xbfb8aa3b, v131
	v_exp_f32_e32 v131, v131
	v_pk_mul_f32 v[136:137], v[2:3], v[136:137]
	v_add_f32_e32 v131, 1.0, v131
	v_rcp_f32_e32 v132, v131
	v_and_b32_e32 v131, 0xffff0000, v133
	v_mul_f32_e32 v131, 0xbfb8aa3b, v131
	v_exp_f32_e32 v131, v131
	v_cvt_pk_bf16_f32 v136, v136, v137
	v_add_f32_e32 v131, 1.0, v131
	v_rcp_f32_e32 v133, v131
	s_nop 0
	v_pk_mul_f32 v[132:133], v[4:5], v[132:133]
	s_nop 0
	v_cvt_pk_bf16_f32 v137, v132, v133
	ds_write2_b64 v0, v[134:135], v[136:137] offset0:232 offset1:236
